# v25 + prompt attention units: next queue ticket fetched at the start of the unit epilogue
# baseline (speedup 1.0000x reference)
; #define LAS __attribute__((address_space(3)))
; __device__ __forceinline__ int queue_next(unsigned* ctr, LAS unsigned char* lds) {
;     volatile LAS unsigned* w = (volatile LAS unsigned*)(lds + LDS_CTL);
;     if (threadIdx.x == 0) w[0] = atomicAdd(ctr, 1u);
;     __syncthreads();
;     const int u = (int)w[0];
;     __syncthreads();
;     return u;
.LBB0_871:
	s_mov_b64 s[6:7], exec
	v_readlane_b32 s4, v252, 6
	v_readlane_b32 s5, v252, 7
	s_and_b64 s[4:5], s[6:7], s[4:5]
	s_mov_b64 exec, s[4:5]
	s_cbranch_execz .LBB0_873
	s_cmpk_eq_u32 s100, 0x5a5a
	s_cbranch_scc0 .Lgp_sync
	s_mov_b32 s100, 0
	s_waitcnt vmcnt(8)
	v_mov_b32_e32 v0, v251
	s_branch .Lgp_pub

; #define LAS __attribute__((address_space(3)))
; __device__ __forceinline__ float frcp(float x) { return __builtin_amdgcn_rcpf(x); }
;     ...
;         const float inv = frcp(l);
;         LAS float* X = (LAS float*)L + sub * 4096;
;         if (map == 1) {
; #pragma unroll
;             for (int eb = 0; eb < 4; ++eb)
; #pragma unroll
;                 for (int rg = 0; rg < 16; ++rg) X[(eb * 32 + (rg & 3) + 8 * (rg >> 2) + 4 * hi) * 32 + r] = OT[eb][rg] * inv;
;         }
; __device__ __forceinline__ int queue_next(unsigned* ctr, LAS unsigned char* lds) {
;     volatile LAS unsigned* w = (volatile LAS unsigned*)(lds + LDS_CTL);
;     if (threadIdx.x == 0) w[0] = atomicAdd(ctr, 1u);
.LBB0_939:
	s_mov_b64 s[98:99], exec
	v_cmp_eq_u32_e32 vcc, 0, v208
	s_and_b64 exec, s[98:99], vcc
	s_cbranch_execz .Lpp_skip
	global_atomic_add v251, v1, v165, s[52:53] sc0
.Lpp_skip:
	s_mov_b64 exec, s[98:99]
	s_movk_i32 s100, 0x5a5a
	ds_bpermute_b32 v0, v171, v159
	s_lshl_b32 s6, s10, 14
	s_add_i32 s6, s6, 0
	v_lshlrev_b32_e32 v66, 2, v149
	v_lshlrev_b32_e32 v67, 9, v152
	s_waitcnt lgkmcnt(0)
	v_add_f32_e32 v0, v159, v0
	v_rcp_f32_e32 v0, v0
	s_cmp_lg_u32 s9, 1
	v_add3_u32 v66, s6, v66, v67
	s_cbranch_scc1 .LBB0_941
	v_mul_f32_e32 v67, v50, v0
	v_mul_f32_e32 v68, v51, v0
	ds_write2_b32 v66, v67, v68 offset1:32
	v_mul_f32_e32 v67, v52, v0
	v_mul_f32_e32 v68, v53, v0
	ds_write2_b32 v66, v67, v68 offset0:64 offset1:96
	v_mul_f32_e32 v67, v54, v0
	v_mul_f32_e32 v68, v55, v0
	v_add_u32_e32 v69, 0x400, v66
	ds_write2_b32 v69, v67, v68 offset1:32
	v_mul_f32_e32 v67, v56, v0
	v_mul_f32_e32 v68, v57, v0
	ds_write2_b32 v69, v67, v68 offset0:64 offset1:96
	v_mul_f32_e32 v67, v58, v0
	v_mul_f32_e32 v68, v59, v0
	v_add_u32_e32 v69, 0x800, v66
	ds_write2_b32 v69, v67, v68 offset1:32
	v_mul_f32_e32 v67, v60, v0
	v_mul_f32_e32 v68, v61, v0
	ds_write2_b32 v69, v67, v68 offset0:64 offset1:96
	v_mul_f32_e32 v67, v62, v0
	v_mul_f32_e32 v68, v63, v0
	v_add_u32_e32 v69, 0xc00, v66
	ds_write2_b32 v69, v67, v68 offset1:32
	v_mul_f32_e32 v67, v64, v0
	v_mul_f32_e32 v68, v65, v0
	ds_write2_b32 v69, v67, v68 offset0:64 offset1:96
	v_mul_f32_e32 v67, v34, v0
	v_mul_f32_e32 v68, v35, v0
	v_add_u32_e32 v69, 0x1000, v66
	ds_write2_b32 v69, v67, v68 offset1:32
	v_mul_f32_e32 v67, v36, v0
	v_mul_f32_e32 v68, v37, v0
	ds_write2_b32 v69, v67, v68 offset0:64 offset1:96
	v_mul_f32_e32 v67, v38, v0
	v_mul_f32_e32 v68, v39, v0
	v_add_u32_e32 v69, 0x1400, v66
	ds_write2_b32 v69, v67, v68 offset1:32
	v_mul_f32_e32 v67, v40, v0
	v_mul_f32_e32 v68, v41, v0
	ds_write2_b32 v69, v67, v68 offset0:64 offset1:96
	v_mul_f32_e32 v67, v42, v0
	v_mul_f32_e32 v68, v43, v0
	v_add_u32_e32 v69, 0x1800, v66
	ds_write2_b32 v69, v67, v68 offset1:32
	v_mul_f32_e32 v67, v44, v0
	v_mul_f32_e32 v68, v45, v0
	ds_write2_b32 v69, v67, v68 offset0:64 offset1:96
	v_mul_f32_e32 v67, v46, v0
	v_mul_f32_e32 v68, v47, v0
	v_add_u32_e32 v69, 0x1c00, v66
	ds_write2_b32 v69, v67, v68 offset1:32
	v_mul_f32_e32 v67, v48, v0
	v_mul_f32_e32 v68, v49, v0
	ds_write2_b32 v69, v67, v68 offset0:64 offset1:96
	v_mul_f32_e32 v67, v18, v0
	v_mul_f32_e32 v68, v19, v0
	v_add_u32_e32 v69, 0x2000, v66
	ds_write2_b32 v69, v67, v68 offset1:32
	v_mul_f32_e32 v67, v20, v0
	v_mul_f32_e32 v68, v21, v0
	ds_write2_b32 v69, v67, v68 offset0:64 offset1:96
	v_mul_f32_e32 v67, v22, v0
	v_mul_f32_e32 v68, v23, v0
	v_add_u32_e32 v69, 0x2400, v66
	ds_write2_b32 v69, v67, v68 offset1:32
	v_mul_f32_e32 v67, v24, v0
	v_mul_f32_e32 v68, v25, v0
	ds_write2_b32 v69, v67, v68 offset0:64 offset1:96
	v_mul_f32_e32 v67, v26, v0
	v_mul_f32_e32 v68, v27, v0
	v_add_u32_e32 v69, 0x2800, v66
	ds_write2_b32 v69, v67, v68 offset1:32
	v_mul_f32_e32 v67, v28, v0
	v_mul_f32_e32 v68, v29, v0
	ds_write2_b32 v69, v67, v68 offset0:64 offset1:96
	v_mul_f32_e32 v67, v30, v0
	v_mul_f32_e32 v68, v31, v0
	v_add_u32_e32 v69, 0x2c00, v66
	ds_write2_b32 v69, v67, v68 offset1:32
	v_mul_f32_e32 v67, v32, v0
	v_mul_f32_e32 v68, v33, v0
	ds_write2_b32 v69, v67, v68 offset0:64 offset1:96
	v_mul_f32_e32 v67, v2, v0
	v_mul_f32_e32 v68, v3, v0
	v_add_u32_e32 v69, 0x3000, v66
	ds_write2_b32 v69, v67, v68 offset1:32
	v_mul_f32_e32 v67, v4, v0
	v_mul_f32_e32 v68, v5, v0
	ds_write2_b32 v69, v67, v68 offset0:64 offset1:96
	v_mul_f32_e32 v67, v6, v0
	v_mul_f32_e32 v68, v7, v0
	v_add_u32_e32 v69, 0x3400, v66
	ds_write2_b32 v69, v67, v68 offset1:32
	v_mul_f32_e32 v67, v8, v0
	v_mul_f32_e32 v68, v9, v0
	ds_write2_b32 v69, v67, v68 offset0:64 offset1:96
	v_mul_f32_e32 v67, v10, v0
	v_mul_f32_e32 v68, v11, v0
	v_add_u32_e32 v69, 0x3800, v66
	ds_write2_b32 v69, v67, v68 offset1:32
	v_mul_f32_e32 v67, v12, v0
	v_mul_f32_e32 v68, v13, v0
	ds_write2_b32 v69, v67, v68 offset0:64 offset1:96
	v_mul_f32_e32 v67, v14, v0
	v_mul_f32_e32 v68, v15, v0
	v_add_u32_e32 v69, 0x3c00, v66
	ds_write2_b32 v69, v67, v68 offset1:32
	v_mul_f32_e32 v67, v16, v0
	v_mul_f32_e32 v68, v17, v0
	ds_write2_b32 v69, v67, v68 offset0:64 offset1:96
